# NA loop: 32 exec-masked individually-waited bias lookups replaced by a rolling window of 8 LDS reads + v_cndmask (de-waterfall)
# speedup vs baseline: 1.0127x; 1.0117x over previous
; DEV int crow_of(int reg, int h) { return (reg & 3) + 8 * (reg >> 2) + 4 * h; }
; template <int DQK, int DV, int NKH, int MODE>
; DEV void flash_unit(const FlashArgs& fa, char* smem, f32x16 (&oacc)[DV / 32], float& linv_out) {
;     ...
;       if (MODE == 1 && it >= 4) {
;         const int dr = krow - na_row + 7;
;         const float* bp = rpbs + dr * 31;
; #pragma unroll
;         for (int k2 = 0; k2 < 2; ++k2)
; #pragma unroll
;           for (int e = 0; e < 16; ++e) {
;             const int kc = k2 * 32 + crow_of(e, h);
;             const bool valid = (kc >= na_cstart) && (kc < na_cstart + 16);
;             const int idx = min(max(kc - na_qc + 15, 0), 30);
;             const float bv = bp[idx];
;             st[k2][e] = valid ? st[k2][e] + bv : -1e30f;
;           }
;       }
.LBB0_259:
	s_andn2_b64 vcc, exec, s[28:29]
	s_cbranch_vccnz .LBB0_325
	v_mov_b32_e32 v243, 0xf149f2ca
	v_add_u32_e32 v96, v149, v195
	v_add_u32_e32 v97, v149, v194
	v_add_u32_e32 v98, v149, v193
	v_add_u32_e32 v99, v149, v192
	v_add_u32_e32 v100, v149, v191
	v_add_u32_e32 v101, v149, v190
	v_add_u32_e32 v102, v149, v189
	v_add_u32_e32 v103, v149, v188
	ds_read_b32 v96, v96
	ds_read_b32 v97, v97
	ds_read_b32 v98, v98
	ds_read_b32 v99, v99
	ds_read_b32 v100, v100
	ds_read_b32 v101, v101
	ds_read_b32 v102, v102
	ds_read_b32 v103, v103
	v_add_u32_e32 v104, v149, v187
	s_waitcnt lgkmcnt(7)
	v_add_f32_e32 v96, v64, v96
	ds_read_b32 v104, v104
	v_cndmask_b32_e64 v96, v243, v96, s[38:39]
	v_add_u32_e32 v105, v149, v186
	s_waitcnt lgkmcnt(7)
	v_add_f32_e32 v97, v65, v97
	ds_read_b32 v105, v105
	v_cndmask_b32_e64 v97, v243, v97, s[40:41]
	v_add_u32_e32 v106, v149, v185
	s_waitcnt lgkmcnt(7)
	v_add_f32_e32 v98, v66, v98
	ds_read_b32 v106, v106
	v_cndmask_b32_e64 v98, v243, v98, s[42:43]
	v_add_u32_e32 v107, v149, v184
	s_waitcnt lgkmcnt(7)
	v_add_f32_e32 v99, v67, v99
	ds_read_b32 v107, v107
	v_cndmask_b32_e64 v99, v243, v99, s[44:45]
	v_add_u32_e32 v108, v149, v183
	s_waitcnt lgkmcnt(7)
	v_add_f32_e32 v100, v68, v100
	ds_read_b32 v108, v108
	v_cndmask_b32_e64 v100, v243, v100, s[46:47]
	v_add_u32_e32 v109, v149, v182
	s_waitcnt lgkmcnt(7)
	v_add_f32_e32 v101, v69, v101
	ds_read_b32 v109, v109
	v_cndmask_b32_e64 v101, v243, v101, s[48:49]
	v_add_u32_e32 v110, v149, v181
	s_waitcnt lgkmcnt(7)
	v_add_f32_e32 v102, v70, v102
	ds_read_b32 v110, v110
	v_cndmask_b32_e64 v102, v243, v102, s[50:51]
	v_add_u32_e32 v111, v149, v165
	s_waitcnt lgkmcnt(7)
	v_add_f32_e32 v103, v71, v103
	ds_read_b32 v111, v111
	v_cndmask_b32_e64 v103, v243, v103, s[52:53]
	v_add_u32_e32 v116, v149, v164
	s_waitcnt lgkmcnt(7)
	v_add_f32_e32 v104, v72, v104
	ds_read_b32 v116, v116
	v_cndmask_b32_e64 v104, v243, v104, s[86:87]
	v_add_u32_e32 v117, v149, v163
	s_waitcnt lgkmcnt(7)
	v_add_f32_e32 v105, v73, v105
	ds_read_b32 v117, v117
	v_cndmask_b32_e64 v105, v243, v105, s[88:89]
	v_add_u32_e32 v118, v149, v162
	s_waitcnt lgkmcnt(7)
	v_add_f32_e32 v106, v74, v106
	ds_read_b32 v118, v118
	v_cndmask_b32_e64 v106, v243, v106, s[90:91]
	v_add_u32_e32 v119, v149, v161
	s_waitcnt lgkmcnt(7)
	v_add_f32_e32 v107, v75, v107
	ds_read_b32 v119, v119
	v_cndmask_b32_e64 v107, v243, v107, s[4:5]
	v_add_u32_e32 v120, v149, v160
	s_waitcnt lgkmcnt(7)
	v_add_f32_e32 v108, v76, v108
	ds_read_b32 v120, v120
	v_cndmask_b32_e64 v108, v243, v108, s[6:7]
	v_add_u32_e32 v121, v149, v159
	s_waitcnt lgkmcnt(7)
	v_add_f32_e32 v109, v77, v109
	ds_read_b32 v121, v121
	v_cndmask_b32_e64 v109, v243, v109, s[8:9]
	v_add_u32_e32 v122, v149, v158
	s_waitcnt lgkmcnt(7)
	v_add_f32_e32 v110, v78, v110
	ds_read_b32 v122, v122
	v_cndmask_b32_e64 v110, v243, v110, s[10:11]
	v_add_u32_e32 v123, v149, v157
	s_waitcnt lgkmcnt(7)
	v_add_f32_e32 v111, v79, v111
	ds_read_b32 v123, v123
	v_cndmask_b32_e64 v111, v243, v111, s[12:13]
	v_add_u32_e32 v124, v149, v156
	s_waitcnt lgkmcnt(7)
	v_add_f32_e32 v116, v48, v116
	ds_read_b32 v124, v124
	v_cndmask_b32_e64 v116, v243, v116, s[14:15]
	v_add_u32_e32 v125, v149, v155
	s_waitcnt lgkmcnt(7)
	v_add_f32_e32 v117, v49, v117
	ds_read_b32 v125, v125
	v_cndmask_b32_e64 v117, v243, v117, s[16:17]
	v_add_u32_e32 v126, v149, v154
	s_waitcnt lgkmcnt(7)
	v_add_f32_e32 v118, v50, v118
	ds_read_b32 v126, v126
	v_cndmask_b32_e64 v118, v243, v118, s[18:19]
	v_add_u32_e32 v127, v149, v153
	s_waitcnt lgkmcnt(7)
	v_add_f32_e32 v119, v51, v119
	ds_read_b32 v127, v127
	v_cndmask_b32_e64 v119, v243, v119, s[20:21]
	v_add_u32_e32 v128, v149, v152
	s_waitcnt lgkmcnt(7)
	v_add_f32_e32 v120, v52, v120
	ds_read_b32 v128, v128
	v_cndmask_b32_e64 v120, v243, v120, s[22:23]
	v_add_u32_e32 v129, v149, v151
	s_waitcnt lgkmcnt(7)
	v_add_f32_e32 v121, v53, v121
	ds_read_b32 v129, v129
	v_cndmask_b32_e64 v121, v243, v121, s[24:25]
	v_add_u32_e32 v130, v149, v150
	s_waitcnt lgkmcnt(7)
	v_add_f32_e32 v122, v54, v122
	ds_read_b32 v130, v130
	v_cndmask_b32_e64 v122, v243, v122, s[26:27]
	v_add_u32_e32 v131, v149, v148
	s_waitcnt lgkmcnt(7)
	v_add_f32_e32 v123, v55, v123
	ds_read_b32 v131, v131
	v_cndmask_b32_e64 v123, v243, v123, s[72:73]
	s_waitcnt lgkmcnt(7)
	v_add_f32_e32 v124, v56, v124
	v_cndmask_b32_e64 v124, v243, v124, s[54:55]
	s_waitcnt lgkmcnt(6)
	v_add_f32_e32 v125, v57, v125
	v_cndmask_b32_e64 v125, v243, v125, s[56:57]
	s_waitcnt lgkmcnt(5)
	v_add_f32_e32 v126, v58, v126
	v_cndmask_b32_e64 v126, v243, v126, s[58:59]
	s_waitcnt lgkmcnt(4)
	v_add_f32_e32 v127, v59, v127
	v_cndmask_b32_e64 v127, v243, v127, s[60:61]
	s_waitcnt lgkmcnt(3)
	v_add_f32_e32 v128, v60, v128
	v_cndmask_b32_e64 v128, v243, v128, s[62:63]
	s_waitcnt lgkmcnt(2)
	v_add_f32_e32 v129, v61, v129
	v_cndmask_b32_e64 v129, v243, v129, s[64:65]
	s_waitcnt lgkmcnt(1)
	v_add_f32_e32 v130, v62, v130
	v_cndmask_b32_e64 v130, v243, v130, s[66:67]
	s_waitcnt lgkmcnt(0)
	v_add_f32_e32 v131, v63, v131
	v_cndmask_b32_e64 v131, v243, v131, s[68:69]
	s_branch .LBB0_326
